# plus phase 3 unit assignment: second-round column tiles swapped pairwise so every workgroup gets one heavy and one light epilogue (log-decay+plain, silu+silu)
# baseline (speedup 1.0000x reference)
;     __host__ __device__ bool next(int i, Unit& u) const {
;         const long L = (long)i * G + c; if (L >= nwg) return false;
;         int wgid = (int)L; { const int q = nwg / NXCD, r = nwg % NXCD, xcd = wgid % NXCD, off = wgid / NXCD; wgid = (xcd < r ? xcd * (q + 1) : r * (q + 1) + (xcd - r) * q) + off; }
;         const int nig = WGM * nN, gid = wgid / nig, fm = gid * WGM, gsz = (nM - fm) < WGM ? (nM - fm) : WGM;
;         u.pm = fm + ((wgid % nig) % gsz); u.pn = (wgid % nig) / gsz; return true;
;     }
.LBB0_460:
	s_ashr_i32 s7, s7, 3
	s_add_i32 s7, s67, s7
	s_ashr_i32 s52, s7, 31
	s_lshr_b32 s52, s52, 26
	s_add_i32 s52, s7, s52
	s_ashr_i32 s53, s52, 6
	s_lshl_b32 s53, s53, 3
	s_sub_i32 s64, 64, s53
	s_min_i32 s65, s64, 8
	s_andn2_b32 s52, s52, 63
	s_sub_i32 s7, s7, s52
	s_lshr_b32 s64, s7, 3
	s_and_b32 s52, s64, 4
	s_lshr_b32 s52, s52, 1
	s_xor_b32 s64, s64, s52
	s_and_b32 s7, s7, 7
	s_add_i32 s66, s53, s7
